# GLU epilogue: operand loads of batches 1 and 3 issued one batch early into spare VGPRs (next_free_vgpr 256)
# baseline (speedup 1.0000x reference)
.LBB0_402:
	v_lshl_add_u32 v184, s76, 8, v212
	v_lshl_or_b32 v186, s77, 8, v214
	v_readlane_b32 s72, v233, 21
	v_ashrrev_i32_e32 v187, 31, v186
	v_readlane_b32 s84, v233, 33
	v_readlane_b32 s85, v233, 34
	v_or_b32_e32 v202, 48, v184
	v_lshlrev_b64 v[190:191], 1, v[186:187]
	v_lshl_add_u64 v[188:189], v[186:187], 2, s[84:85]
	global_load_dwordx4 v[88:91], v[188:189], off offset:16
	global_load_dwordx4 v[92:95], v[188:189], off
	v_ashrrev_i32_e32 v203, 31, v202
	v_lshl_add_u64 v[208:209], s[20:21], 0, v[190:191]
	v_lshl_add_u64 v[206:207], s[36:37], 0, v[190:191]
	v_ashrrev_i32_e32 v185, 31, v184
	v_lshlrev_b64 v[204:205], 12, v[202:203]
	v_mad_i64_i32 v[128:129], s[4:5], v184, s67, v[208:209]
	v_lshlrev_b64 v[192:193], 12, v[184:185]
	v_lshl_add_u64 v[132:133], v[206:207], 0, v[204:205]
	global_load_dwordx4 v[160:163], v[128:129], off nt
	v_or_b32_e32 v196, 16, v184
	global_load_dwordx4 v[132:135], v[132:133], off nt
	v_lshl_add_u64 v[128:129], v[206:207], 0, v[192:193]
	global_load_dwordx4 v[164:167], v[128:129], off nt
	v_ashrrev_i32_e32 v197, 31, v196
	v_mad_i64_i32 v[128:129], s[4:5], v196, s67, v[208:209]
	v_lshlrev_b64 v[194:195], 12, v[196:197]
	global_load_dwordx4 v[152:155], v[128:129], off nt
	v_lshl_add_u64 v[128:129], v[206:207], 0, v[194:195]
	global_load_dwordx4 v[156:159], v[128:129], off nt
	v_or_b32_e32 v200, 32, v184
	v_ashrrev_i32_e32 v201, 31, v200
	v_mad_i64_i32 v[128:129], s[4:5], v200, s67, v[208:209]
	v_lshlrev_b64 v[198:199], 12, v[200:201]
	global_load_dwordx4 v[136:139], v[128:129], off nt
	v_lshl_add_u64 v[128:129], v[206:207], 0, v[198:199]
	global_load_dwordx4 v[140:143], v[128:129], off nt
	v_mad_i64_i32 v[128:129], s[4:5], v202, s67, v[208:209]
	global_load_dwordx4 v[128:131], v[128:129], off nt
	v_add_u32_e32 v230, 0x80, v184
	v_mad_i64_i32 v[238:239], s[98:99], v230, s67, v[208:209]
	global_load_dwordx4 v[218:221], v[238:239], off nt
	v_ashrrev_i32_e32 v231, 31, v230
	v_lshlrev_b64 v[230:231], 12, v[230:231]
	v_lshl_add_u64 v[230:231], v[206:207], 0, v[230:231]
	global_load_dwordx4 v[222:225], v[230:231], off nt
	v_add_u32_e32 v230, 0x90, v184
	v_mad_i64_i32 v[238:239], s[98:99], v230, s67, v[208:209]
	global_load_dwordx4 v[226:229], v[238:239], off nt
	v_ashrrev_i32_e32 v231, 31, v230
	v_lshlrev_b64 v[230:231], 12, v[230:231]
	v_lshl_add_u64 v[230:231], v[206:207], 0, v[230:231]
	global_load_dwordx4 v[234:237], v[230:231], off nt
	v_add_u32_e32 v230, 0xa0, v184
	v_mad_i64_i32 v[238:239], s[98:99], v230, s67, v[208:209]
	global_load_dwordx4 v[240:243], v[238:239], off nt
	v_ashrrev_i32_e32 v231, 31, v230
	v_lshlrev_b64 v[230:231], 12, v[230:231]
	v_lshl_add_u64 v[230:231], v[206:207], 0, v[230:231]
	global_load_dwordx4 v[244:247], v[230:231], off nt
	v_add_u32_e32 v230, 0xb0, v184
	v_mad_i64_i32 v[238:239], s[98:99], v230, s67, v[208:209]
	global_load_dwordx4 v[248:251], v[238:239], off nt
	v_ashrrev_i32_e32 v231, 31, v230
	v_lshlrev_b64 v[230:231], 12, v[230:231]
	v_lshl_add_u64 v[230:231], v[206:207], 0, v[230:231]
	global_load_dwordx4 v[252:255], v[230:231], off nt
	s_and_b64 vcc, exec, s[38:39]
	v_readlane_b32 s73, v233, 22
	v_readlane_b32 s74, v233, 23
	v_readlane_b32 s75, v233, 24
	v_readlane_b32 s76, v233, 25
	v_readlane_b32 s77, v233, 26
	v_readlane_b32 s78, v233, 27
	v_readlane_b32 s79, v233, 28
	v_readlane_b32 s80, v233, 29
	v_readlane_b32 s81, v233, 30
	v_readlane_b32 s82, v233, 31
	v_readlane_b32 s83, v233, 32
	v_readlane_b32 s86, v233, 35
	v_readlane_b32 s87, v233, 36
	s_waitcnt vmcnt(0)
	v_pk_add_f32 v[144:145], v[144:145], v[88:89]
	v_pk_add_f32 v[148:149], v[148:149], v[92:93]
	v_pk_add_f32 v[150:151], v[150:151], v[94:95]
	v_mul_f32_e32 v149, 0xbfb8aa3b, v149
	v_exp_f32_e32 v149, v149
	v_mul_f32_e32 v150, 0xbfb8aa3b, v150
	v_exp_f32_e32 v150, v150
	v_mul_f32_e32 v151, 0xbfb8aa3b, v151
	v_add_f32_e32 v149, 1.0, v149
	v_exp_f32_e32 v151, v151
	v_rcp_f32_e32 v149, v149
	v_mul_f32_e32 v144, 0xbfb8aa3b, v144
	v_add_f32_e32 v150, 1.0, v150
	v_exp_f32_e32 v144, v144
	v_lshlrev_b32_e32 v187, 16, v160
	v_lshlrev_b32_e32 v185, 16, v164
	v_and_b32_e32 v164, 0xffff0000, v164
	v_and_b32_e32 v160, 0xffff0000, v160
	v_rcp_f32_e32 v150, v150
	v_mul_f32_e32 v145, 0xbfb8aa3b, v145
	v_pk_add_f32 v[146:147], v[146:147], v[90:91]
	v_mul_f32_e32 v160, v164, v160
	v_add_f32_e32 v151, 1.0, v151
	v_exp_f32_e32 v145, v145
	v_mul_f32_e32 v149, v149, v160
	v_lshlrev_b32_e32 v160, 16, v165
	v_lshlrev_b32_e32 v164, 16, v161
	v_rcp_f32_e32 v151, v151
	v_mul_f32_e32 v146, 0xbfb8aa3b, v146
	v_mul_f32_e32 v148, 0xbfb8aa3b, v148
	v_mul_f32_e32 v160, v160, v164
	v_add_f32_e32 v144, 1.0, v144
	v_exp_f32_e32 v146, v146
	v_exp_f32_e32 v148, v148
	v_mul_f32_e32 v150, v150, v160
	v_and_b32_e32 v160, 0xffff0000, v165
	v_and_b32_e32 v161, 0xffff0000, v161
	v_rcp_f32_e32 v144, v144
	v_mul_f32_e32 v147, 0xbfb8aa3b, v147
	v_mul_f32_e32 v160, v160, v161
	v_add_f32_e32 v145, 1.0, v145
	v_exp_f32_e32 v147, v147
	v_mul_f32_e32 v151, v151, v160
	v_lshlrev_b32_e32 v160, 16, v166
	v_lshlrev_b32_e32 v161, 16, v162
	v_rcp_f32_e32 v145, v145
	v_mul_f32_e32 v160, v160, v161
	v_add_f32_e32 v146, 1.0, v146
	v_pk_add_f32 v[124:125], v[124:125], v[92:93]
	v_add_f32_e32 v148, 1.0, v148
	v_mul_f32_e32 v144, v160, v144
	v_and_b32_e32 v160, 0xffff0000, v166
	v_and_b32_e32 v161, 0xffff0000, v162
	v_rcp_f32_e32 v146, v146
	v_mul_f32_e32 v124, 0xbfb8aa3b, v124
	v_rcp_f32_e32 v148, v148
	v_mul_f32_e32 v160, v160, v161
	v_add_f32_e32 v147, 1.0, v147
	v_exp_f32_e32 v124, v124
	v_mul_f32_e32 v145, v160, v145
	v_lshlrev_b32_e32 v160, 16, v167
	v_lshlrev_b32_e32 v161, 16, v163
	v_rcp_f32_e32 v147, v147
	v_mul_f32_e32 v125, 0xbfb8aa3b, v125
	v_mul_f32_e32 v160, v160, v161
	v_pk_add_f32 v[126:127], v[126:127], v[94:95]
	v_exp_f32_e32 v125, v125
	v_mul_f32_e32 v185, v185, v187
	v_mul_f32_e32 v160, v160, v146
	v_and_b32_e32 v146, 0xffff0000, v167
	v_and_b32_e32 v161, 0xffff0000, v163
	v_mul_f32_e32 v126, 0xbfb8aa3b, v126
	v_mul_f32_e32 v148, v148, v185
	v_mul_f32_e32 v146, v146, v161
	v_add_f32_e32 v124, 1.0, v124
	v_exp_f32_e32 v126, v126
	v_mul_f32_e32 v161, v146, v147
	v_cvt_pk_bf16_f32 v146, v148, v149
	v_cvt_pk_bf16_f32 v147, v150, v151
	v_cvt_pk_bf16_f32 v148, v144, v145
	v_lshl_add_u64 v[144:145], s[18:19], 0, v[192:193]
	v_rcp_f32_e32 v124, v124
	v_mul_f32_e32 v127, 0xbfb8aa3b, v127
	v_lshl_add_u64 v[144:145], v[144:145], 0, v[190:191]
	v_pk_add_f32 v[120:121], v[120:121], v[88:89]
	v_add_f32_e32 v125, 1.0, v125
	v_exp_f32_e32 v127, v127
	v_cvt_pk_bf16_f32 v149, v160, v161
	global_store_dwordx4 v[144:145], v[146:149], off
	v_rcp_f32_e32 v125, v125
	v_mul_f32_e32 v120, 0xbfb8aa3b, v120
	v_lshlrev_b32_e32 v146, 16, v156
	v_lshlrev_b32_e32 v147, 16, v152
	v_mul_f32_e32 v146, v146, v147
	v_add_f32_e32 v126, 1.0, v126
	v_exp_f32_e32 v120, v120
	v_mul_f32_e32 v124, v124, v146
	v_and_b32_e32 v146, 0xffff0000, v156
	v_and_b32_e32 v147, 0xffff0000, v152
	v_rcp_f32_e32 v126, v126
	v_mul_f32_e32 v121, 0xbfb8aa3b, v121
	v_mul_f32_e32 v146, v146, v147
	v_add_f32_e32 v127, 1.0, v127
	v_exp_f32_e32 v121, v121
	v_mul_f32_e32 v125, v125, v146
	v_lshlrev_b32_e32 v146, 16, v157
	v_lshlrev_b32_e32 v147, 16, v153
	v_rcp_f32_e32 v127, v127
	v_mul_f32_e32 v146, v146, v147
	v_add_f32_e32 v120, 1.0, v120
	v_mul_f32_e32 v126, v126, v146
	v_and_b32_e32 v146, 0xffff0000, v157
	v_and_b32_e32 v147, 0xffff0000, v153
	v_rcp_f32_e32 v120, v120
	v_mul_f32_e32 v146, v146, v147
	v_add_f32_e32 v121, 1.0, v121
	v_mul_f32_e32 v127, v127, v146
	v_lshlrev_b32_e32 v146, 16, v158
	v_lshlrev_b32_e32 v147, 16, v154
	v_rcp_f32_e32 v121, v121
	v_mul_f32_e32 v146, v146, v147
	v_mul_f32_e32 v146, v120, v146
	v_and_b32_e32 v120, 0xffff0000, v158
	v_and_b32_e32 v147, 0xffff0000, v154
	v_mul_f32_e32 v120, v120, v147
	v_pk_add_f32 v[122:123], v[122:123], v[90:91]
	v_mul_f32_e32 v147, v121, v120
	v_lshlrev_b32_e32 v120, 16, v159
	v_lshlrev_b32_e32 v121, 16, v155
	v_mul_f32_e32 v120, v120, v121
	v_mul_f32_e32 v121, 0xbfb8aa3b, v122
	v_exp_f32_e32 v121, v121
	v_pk_add_f32 v[116:117], v[116:117], v[92:93]
	v_pk_add_f32 v[118:119], v[118:119], v[94:95]
	v_mul_f32_e32 v116, 0xbfb8aa3b, v116
	v_add_f32_e32 v121, 1.0, v121
	v_rcp_f32_e32 v121, v121
	v_exp_f32_e32 v116, v116
	v_mul_f32_e32 v117, 0xbfb8aa3b, v117
	v_exp_f32_e32 v117, v117
	v_mul_f32_e32 v148, v121, v120
	v_and_b32_e32 v120, 0xffff0000, v159
	v_and_b32_e32 v121, 0xffff0000, v155
	v_mul_f32_e32 v120, v120, v121
	v_mul_f32_e32 v121, 0xbfb8aa3b, v123
	v_exp_f32_e32 v121, v121
	v_mul_f32_e32 v118, 0xbfb8aa3b, v118
	v_add_f32_e32 v116, 1.0, v116
	v_exp_f32_e32 v118, v118
	v_add_f32_e32 v121, 1.0, v121
	v_rcp_f32_e32 v121, v121
	v_rcp_f32_e32 v116, v116
	v_mul_f32_e32 v119, 0xbfb8aa3b, v119
	v_pk_add_f32 v[112:113], v[112:113], v[88:89]
	v_mul_f32_e32 v123, v121, v120
	v_cvt_pk_bf16_f32 v120, v124, v125
	v_lshl_add_u64 v[124:125], s[18:19], 0, v[194:195]
	v_cvt_pk_bf16_f32 v121, v126, v127
	v_cvt_pk_bf16_f32 v122, v146, v147
	v_lshl_add_u64 v[146:147], v[124:125], 0, v[190:191]
	v_add_f32_e32 v117, 1.0, v117
	v_exp_f32_e32 v119, v119
	v_cvt_pk_bf16_f32 v123, v148, v123
	global_store_dwordx4 v[146:147], v[120:123], off
	v_rcp_f32_e32 v117, v117
	v_mul_f32_e32 v112, 0xbfb8aa3b, v112
	v_lshlrev_b32_e32 v120, 16, v140
	v_lshlrev_b32_e32 v121, 16, v136
	v_mul_f32_e32 v120, v120, v121
	v_add_f32_e32 v118, 1.0, v118
	v_exp_f32_e32 v112, v112
	v_mul_f32_e32 v116, v116, v120
	v_and_b32_e32 v120, 0xffff0000, v140
	v_and_b32_e32 v121, 0xffff0000, v136
	v_rcp_f32_e32 v118, v118
	v_mul_f32_e32 v113, 0xbfb8aa3b, v113
	v_mul_f32_e32 v120, v120, v121
	v_add_f32_e32 v119, 1.0, v119
	v_exp_f32_e32 v113, v113
	v_mul_f32_e32 v117, v117, v120
	v_lshlrev_b32_e32 v120, 16, v141
	v_lshlrev_b32_e32 v121, 16, v137
	v_rcp_f32_e32 v119, v119
	v_mul_f32_e32 v120, v120, v121
	v_add_f32_e32 v112, 1.0, v112
	v_mul_f32_e32 v118, v118, v120
	v_and_b32_e32 v120, 0xffff0000, v141
	v_and_b32_e32 v121, 0xffff0000, v137
	v_rcp_f32_e32 v112, v112
	v_mul_f32_e32 v120, v120, v121
	v_add_f32_e32 v113, 1.0, v113
	v_mul_f32_e32 v119, v119, v120
	v_lshlrev_b32_e32 v120, 16, v142
	v_lshlrev_b32_e32 v121, 16, v138
	v_rcp_f32_e32 v113, v113
	v_mul_f32_e32 v120, v120, v121
	v_mul_f32_e32 v120, v112, v120
	v_and_b32_e32 v112, 0xffff0000, v142
	v_and_b32_e32 v121, 0xffff0000, v138
	v_mul_f32_e32 v112, v112, v121
	v_pk_add_f32 v[114:115], v[114:115], v[90:91]
	v_mul_f32_e32 v121, v113, v112
	v_lshlrev_b32_e32 v112, 16, v143
	v_lshlrev_b32_e32 v113, 16, v139
	v_mul_f32_e32 v112, v112, v113
	v_mul_f32_e32 v113, 0xbfb8aa3b, v114
	v_exp_f32_e32 v113, v113
	v_pk_add_f32 v[108:109], v[108:109], v[92:93]
	v_pk_add_f32 v[110:111], v[110:111], v[94:95]
	v_mul_f32_e32 v108, 0xbfb8aa3b, v108
	v_add_f32_e32 v113, 1.0, v113
	v_rcp_f32_e32 v113, v113
	v_exp_f32_e32 v108, v108
	v_mul_f32_e32 v109, 0xbfb8aa3b, v109
	v_exp_f32_e32 v109, v109
	v_mul_f32_e32 v122, v113, v112
	v_and_b32_e32 v112, 0xffff0000, v143
	v_and_b32_e32 v113, 0xffff0000, v139
	v_mul_f32_e32 v112, v112, v113
	v_mul_f32_e32 v113, 0xbfb8aa3b, v115
	v_exp_f32_e32 v113, v113
	v_mul_f32_e32 v110, 0xbfb8aa3b, v110
	v_add_f32_e32 v108, 1.0, v108
	v_exp_f32_e32 v110, v110
	v_add_f32_e32 v113, 1.0, v113
	v_rcp_f32_e32 v113, v113
	v_rcp_f32_e32 v108, v108
	v_mul_f32_e32 v111, 0xbfb8aa3b, v111
	v_pk_add_f32 v[104:105], v[104:105], v[88:89]
	v_mul_f32_e32 v115, v113, v112
	v_cvt_pk_bf16_f32 v112, v116, v117
	v_lshl_add_u64 v[116:117], s[18:19], 0, v[198:199]
	v_cvt_pk_bf16_f32 v113, v118, v119
	v_lshl_add_u64 v[136:137], v[116:117], 0, v[190:191]
	v_add_f32_e32 v109, 1.0, v109
	v_exp_f32_e32 v111, v111
	v_cvt_pk_bf16_f32 v114, v120, v121
	v_cvt_pk_bf16_f32 v115, v122, v115
	global_store_dwordx4 v[136:137], v[112:115], off
	v_rcp_f32_e32 v109, v109
	v_mul_f32_e32 v104, 0xbfb8aa3b, v104
	v_lshlrev_b32_e32 v112, 16, v132
	v_lshlrev_b32_e32 v113, 16, v128
	v_mul_f32_e32 v112, v112, v113
	v_add_f32_e32 v110, 1.0, v110
	v_exp_f32_e32 v104, v104
	v_mul_f32_e32 v108, v108, v112
	v_and_b32_e32 v112, 0xffff0000, v132
	v_and_b32_e32 v113, 0xffff0000, v128
	v_rcp_f32_e32 v110, v110
	v_mul_f32_e32 v105, 0xbfb8aa3b, v105
	v_mul_f32_e32 v112, v112, v113
	v_add_f32_e32 v111, 1.0, v111
	v_exp_f32_e32 v105, v105
	v_mul_f32_e32 v109, v109, v112
	v_lshlrev_b32_e32 v112, 16, v133
	v_lshlrev_b32_e32 v113, 16, v129
	v_rcp_f32_e32 v111, v111
	v_mul_f32_e32 v112, v112, v113
	v_add_f32_e32 v104, 1.0, v104
	v_mul_f32_e32 v110, v110, v112
	v_and_b32_e32 v112, 0xffff0000, v133
	v_and_b32_e32 v113, 0xffff0000, v129
	v_rcp_f32_e32 v104, v104
	v_mul_f32_e32 v112, v112, v113
	v_add_f32_e32 v105, 1.0, v105
	v_mul_f32_e32 v111, v111, v112
	v_lshlrev_b32_e32 v112, 16, v134
	v_lshlrev_b32_e32 v113, 16, v130
	v_rcp_f32_e32 v105, v105
	v_mul_f32_e32 v112, v112, v113
	v_mul_f32_e32 v112, v104, v112
	v_and_b32_e32 v104, 0xffff0000, v134
	v_and_b32_e32 v113, 0xffff0000, v130
	v_mul_f32_e32 v104, v104, v113
	v_pk_add_f32 v[106:107], v[106:107], v[90:91]
	v_mul_f32_e32 v113, v105, v104
	v_lshlrev_b32_e32 v104, 16, v135
	v_lshlrev_b32_e32 v105, 16, v131
	v_mul_f32_e32 v104, v104, v105
	v_mul_f32_e32 v105, 0xbfb8aa3b, v106
	v_exp_f32_e32 v105, v105
	v_add_u32_e32 v156, 0xb0, v184
	v_add_u32_e32 v140, 0x80, v184
	v_ashrrev_i32_e32 v157, 31, v156
	v_add_f32_e32 v105, 1.0, v105
	v_rcp_f32_e32 v105, v105
	v_ashrrev_i32_e32 v141, 31, v140
	v_lshlrev_b64 v[158:159], 12, v[156:157]
	v_lshlrev_b64 v[142:143], 12, v[140:141]
	v_mul_f32_e32 v114, v105, v104
	v_and_b32_e32 v104, 0xffff0000, v135
	v_and_b32_e32 v105, 0xffff0000, v131
	v_mul_f32_e32 v104, v104, v105
	v_mul_f32_e32 v105, 0xbfb8aa3b, v107
	v_exp_f32_e32 v105, v105
	v_add_u32_e32 v148, 0x90, v184
	v_ashrrev_i32_e32 v149, 31, v148
	v_lshlrev_b64 v[150:151], 12, v[148:149]
	v_add_f32_e32 v105, 1.0, v105
	v_rcp_f32_e32 v105, v105
	v_add_u32_e32 v152, 0xa0, v184
	v_ashrrev_i32_e32 v153, 31, v152
	v_lshlrev_b64 v[154:155], 12, v[152:153]
	v_mul_f32_e32 v107, v105, v104
	v_cvt_pk_bf16_f32 v104, v108, v109
	v_lshl_add_u64 v[108:109], s[18:19], 0, v[204:205]
	v_cvt_pk_bf16_f32 v105, v110, v111
	v_lshl_add_u64 v[138:139], v[108:109], 0, v[190:191]
	v_cvt_pk_bf16_f32 v106, v112, v113
	v_cvt_pk_bf16_f32 v107, v114, v107
	global_store_dwordx4 v[138:139], v[104:107], off
	v_lshl_add_u64 v[108:109], v[206:207], 0, v[158:159]
	s_nop 0
	v_mad_i64_i32 v[104:105], s[4:5], v140, s67, v[208:209]
	s_nop 0
	v_lshl_add_u64 v[104:105], v[206:207], 0, v[142:143]
	s_nop 0
	v_mad_i64_i32 v[104:105], s[4:5], v148, s67, v[208:209]
	s_nop 0
	v_lshl_add_u64 v[104:105], v[206:207], 0, v[150:151]
	s_nop 0
	v_mad_i64_i32 v[104:105], s[4:5], v152, s67, v[208:209]
	s_nop 0
	v_lshl_add_u64 v[104:105], v[206:207], 0, v[154:155]
	s_nop 0
	v_pk_add_f32 v[100:101], v[100:101], v[92:93]
	v_pk_add_f32 v[102:103], v[102:103], v[94:95]
	v_mul_f32_e32 v101, 0xbfb8aa3b, v101
	v_exp_f32_e32 v101, v101
	v_mul_f32_e32 v102, 0xbfb8aa3b, v102
	v_exp_f32_e32 v102, v102
	v_mul_f32_e32 v103, 0xbfb8aa3b, v103
	v_pk_add_f32 v[96:97], v[96:97], v[88:89]
	v_add_f32_e32 v101, 1.0, v101
	v_exp_f32_e32 v103, v103
	v_rcp_f32_e32 v101, v101
	v_mul_f32_e32 v96, 0xbfb8aa3b, v96
	v_add_f32_e32 v102, 1.0, v102
	v_exp_f32_e32 v96, v96
	v_rcp_f32_e32 v102, v102
	v_mul_f32_e32 v97, 0xbfb8aa3b, v97
	v_add_f32_e32 v103, 1.0, v103
	v_exp_f32_e32 v97, v97
	v_rcp_f32_e32 v103, v103
	v_add_f32_e32 v96, 1.0, v96
	v_rcp_f32_e32 v96, v96
	v_add_f32_e32 v97, 1.0, v97
	v_rcp_f32_e32 v97, v97
	v_pk_add_f32 v[98:99], v[98:99], v[90:91]
	v_mul_f32_e32 v100, 0xbfb8aa3b, v100
	v_exp_f32_e32 v100, v100
	v_mad_i64_i32 v[104:105], s[4:5], v156, s67, v[208:209]
	v_pk_add_f32 v[84:85], v[84:85], v[92:93]
	s_nop 0
	v_add_f32_e32 v100, 1.0, v100
	v_mul_f32_e32 v84, 0xbfb8aa3b, v84
	v_rcp_f32_e32 v100, v100
	v_exp_f32_e32 v84, v84
	v_mul_f32_e32 v85, 0xbfb8aa3b, v85
	v_pk_add_f32 v[86:87], v[86:87], v[94:95]
	v_exp_f32_e32 v85, v85
	v_mul_f32_e32 v86, 0xbfb8aa3b, v86
	v_add_f32_e32 v84, 1.0, v84
	v_exp_f32_e32 v86, v86
	v_rcp_f32_e32 v84, v84
	v_mul_f32_e32 v87, 0xbfb8aa3b, v87
	v_pk_add_f32 v[80:81], v[80:81], v[88:89]
	v_add_f32_e32 v85, 1.0, v85
	v_exp_f32_e32 v87, v87
	v_rcp_f32_e32 v85, v85
	v_mul_f32_e32 v80, 0xbfb8aa3b, v80
	v_add_f32_e32 v86, 1.0, v86
	v_exp_f32_e32 v80, v80
	v_rcp_f32_e32 v86, v86
	v_mul_f32_e32 v81, 0xbfb8aa3b, v81
	v_add_f32_e32 v87, 1.0, v87
	v_exp_f32_e32 v81, v81
	v_rcp_f32_e32 v87, v87
	v_add_f32_e32 v80, 1.0, v80
	v_rcp_f32_e32 v80, v80
	v_add_f32_e32 v81, 1.0, v81
	v_rcp_f32_e32 v81, v81
	v_pk_add_f32 v[82:83], v[82:83], v[90:91]
	v_pk_add_f32 v[76:77], v[76:77], v[92:93]
	v_pk_add_f32 v[78:79], v[78:79], v[94:95]
	v_mul_f32_e32 v76, 0xbfb8aa3b, v76
	v_exp_f32_e32 v76, v76
	v_mul_f32_e32 v77, 0xbfb8aa3b, v77
	v_exp_f32_e32 v77, v77
	v_mul_f32_e32 v78, 0xbfb8aa3b, v78
	v_add_f32_e32 v76, 1.0, v76
	s_waitcnt vmcnt(4)
	v_lshlrev_b32_e32 v149, 16, v218
	v_and_b32_e32 v128, 0xffff0000, v218
	s_nop 0
	v_lshlrev_b32_e32 v141, 16, v222
	v_and_b32_e32 v132, 0xffff0000, v222
	v_mul_f32_e32 v128, v132, v128
	v_mul_f32_e32 v101, v101, v128
	v_lshlrev_b32_e32 v128, 16, v223
	v_lshlrev_b32_e32 v132, 16, v219
	v_mul_f32_e32 v128, v128, v132
	v_mul_f32_e32 v102, v102, v128
	v_and_b32_e32 v128, 0xffff0000, v223
	v_and_b32_e32 v129, 0xffff0000, v219
	v_mul_f32_e32 v128, v128, v129
	v_mul_f32_e32 v103, v103, v128
	v_lshlrev_b32_e32 v128, 16, v224
	v_lshlrev_b32_e32 v129, 16, v220
	v_mul_f32_e32 v128, v128, v129
	v_mul_f32_e32 v128, v96, v128
	v_and_b32_e32 v96, 0xffff0000, v224
	v_and_b32_e32 v129, 0xffff0000, v220
	v_mul_f32_e32 v96, v96, v129
	v_mul_f32_e32 v129, v97, v96
	v_lshlrev_b32_e32 v96, 16, v225
	v_lshlrev_b32_e32 v97, 16, v221
	v_mul_f32_e32 v96, v96, v97
	v_mul_f32_e32 v97, 0xbfb8aa3b, v98
	v_exp_f32_e32 v97, v97
	v_mul_f32_e32 v141, v141, v149
	v_mul_f32_e32 v100, v100, v141
	v_exp_f32_e32 v78, v78
	v_add_f32_e32 v97, 1.0, v97
	v_rcp_f32_e32 v97, v97
	v_rcp_f32_e32 v76, v76
	v_mul_f32_e32 v79, 0xbfb8aa3b, v79
	v_pk_add_f32 v[72:73], v[72:73], v[88:89]
	v_mul_f32_e32 v130, v97, v96
	v_and_b32_e32 v96, 0xffff0000, v225
	v_and_b32_e32 v97, 0xffff0000, v221
	v_mul_f32_e32 v96, v96, v97
	v_mul_f32_e32 v97, 0xbfb8aa3b, v99
	v_exp_f32_e32 v97, v97
	v_add_f32_e32 v77, 1.0, v77
	v_exp_f32_e32 v79, v79
	v_rcp_f32_e32 v77, v77
	v_add_f32_e32 v97, 1.0, v97
	v_rcp_f32_e32 v97, v97
	v_mul_f32_e32 v72, 0xbfb8aa3b, v72
	v_add_f32_e32 v78, 1.0, v78
	v_exp_f32_e32 v72, v72
	v_mul_f32_e32 v99, v97, v96
	v_cvt_pk_bf16_f32 v96, v100, v101
	v_lshl_add_u64 v[100:101], s[18:19], 0, v[142:143]
	v_cvt_pk_bf16_f32 v97, v102, v103
	v_cvt_pk_bf16_f32 v98, v128, v129
	v_lshl_add_u64 v[128:129], v[100:101], 0, v[190:191]
	v_cvt_pk_bf16_f32 v99, v130, v99
	global_store_dwordx4 v[128:129], v[96:99], off
	v_rcp_f32_e32 v78, v78
	v_mul_f32_e32 v73, 0xbfb8aa3b, v73
	s_nop 0
	v_lshlrev_b32_e32 v96, 16, v234
	v_lshlrev_b32_e32 v97, 16, v226
	v_mul_f32_e32 v96, v96, v97
	v_mul_f32_e32 v84, v84, v96
	v_and_b32_e32 v96, 0xffff0000, v234
	v_and_b32_e32 v97, 0xffff0000, v226
	v_mul_f32_e32 v96, v96, v97
	v_mul_f32_e32 v85, v85, v96
	v_lshlrev_b32_e32 v96, 16, v235
	v_lshlrev_b32_e32 v97, 16, v227
	v_mul_f32_e32 v96, v96, v97
	v_mul_f32_e32 v86, v86, v96
	v_and_b32_e32 v96, 0xffff0000, v235
	v_and_b32_e32 v97, 0xffff0000, v227
	v_mul_f32_e32 v96, v96, v97
	v_mul_f32_e32 v87, v87, v96
	v_lshlrev_b32_e32 v96, 16, v236
	v_lshlrev_b32_e32 v97, 16, v228
	v_mul_f32_e32 v96, v96, v97
	v_mul_f32_e32 v96, v80, v96
	v_and_b32_e32 v80, 0xffff0000, v236
	v_and_b32_e32 v97, 0xffff0000, v228
	v_mul_f32_e32 v80, v80, v97
	v_mul_f32_e32 v97, v81, v80
	v_lshlrev_b32_e32 v80, 16, v237
	v_lshlrev_b32_e32 v81, 16, v229
	v_mul_f32_e32 v80, v80, v81
	v_mul_f32_e32 v81, 0xbfb8aa3b, v82
	v_exp_f32_e32 v81, v81
	v_add_f32_e32 v79, 1.0, v79
	v_exp_f32_e32 v73, v73
	v_rcp_f32_e32 v79, v79
	v_add_f32_e32 v81, 1.0, v81
	v_rcp_f32_e32 v81, v81
	v_add_f32_e32 v72, 1.0, v72
	v_rcp_f32_e32 v72, v72
	v_add_f32_e32 v73, 1.0, v73
	v_mul_f32_e32 v98, v81, v80
	v_and_b32_e32 v80, 0xffff0000, v237
	v_and_b32_e32 v81, 0xffff0000, v229
	v_mul_f32_e32 v80, v80, v81
	v_mul_f32_e32 v81, 0xbfb8aa3b, v83
	v_exp_f32_e32 v81, v81
	v_rcp_f32_e32 v73, v73
	v_pk_add_f32 v[74:75], v[74:75], v[90:91]
	v_pk_add_f32 v[68:69], v[68:69], v[92:93]
	v_add_f32_e32 v81, 1.0, v81
	v_rcp_f32_e32 v81, v81
	v_mul_f32_e32 v68, 0xbfb8aa3b, v68
	v_exp_f32_e32 v68, v68
	v_mul_f32_e32 v69, 0xbfb8aa3b, v69
	v_mul_f32_e32 v83, v81, v80
	v_cvt_pk_bf16_f32 v80, v84, v85
	v_lshl_add_u64 v[84:85], s[18:19], 0, v[150:151]
	v_cvt_pk_bf16_f32 v81, v86, v87
	v_lshl_add_u64 v[120:121], v[84:85], 0, v[190:191]
	v_cvt_pk_bf16_f32 v82, v96, v97
	v_cvt_pk_bf16_f32 v83, v98, v83
	global_store_dwordx4 v[120:121], v[80:83], off
	v_pk_add_f32 v[70:71], v[70:71], v[94:95]
	v_exp_f32_e32 v69, v69
	s_nop 0
	v_lshlrev_b32_e32 v80, 16, v244
	v_lshlrev_b32_e32 v81, 16, v240
	v_mul_f32_e32 v80, v80, v81
	v_mul_f32_e32 v76, v76, v80
	v_and_b32_e32 v80, 0xffff0000, v244
	v_and_b32_e32 v81, 0xffff0000, v240
	v_mul_f32_e32 v80, v80, v81
	v_mul_f32_e32 v77, v77, v80
	v_lshlrev_b32_e32 v80, 16, v245
	v_lshlrev_b32_e32 v81, 16, v241
	v_mul_f32_e32 v80, v80, v81
	v_mul_f32_e32 v78, v78, v80
	v_and_b32_e32 v80, 0xffff0000, v245
	v_and_b32_e32 v81, 0xffff0000, v241
	v_mul_f32_e32 v80, v80, v81
	v_mul_f32_e32 v79, v79, v80
	v_lshlrev_b32_e32 v80, 16, v246
	v_lshlrev_b32_e32 v81, 16, v242
	v_mul_f32_e32 v80, v80, v81
	v_mul_f32_e32 v80, v72, v80
	v_and_b32_e32 v72, 0xffff0000, v246
	v_and_b32_e32 v81, 0xffff0000, v242
	v_mul_f32_e32 v72, v72, v81
	v_mul_f32_e32 v81, v73, v72
	v_lshlrev_b32_e32 v72, 16, v247
	v_lshlrev_b32_e32 v73, 16, v243
	v_mul_f32_e32 v72, v72, v73
	v_mul_f32_e32 v73, 0xbfb8aa3b, v74
	v_exp_f32_e32 v73, v73
	v_mul_f32_e32 v70, 0xbfb8aa3b, v70
	v_add_f32_e32 v68, 1.0, v68
	v_exp_f32_e32 v70, v70
	v_add_f32_e32 v73, 1.0, v73
	v_rcp_f32_e32 v73, v73
	v_rcp_f32_e32 v68, v68
	v_mul_f32_e32 v71, 0xbfb8aa3b, v71
	v_pk_add_f32 v[64:65], v[64:65], v[88:89]
	v_mul_f32_e32 v82, v73, v72
	v_and_b32_e32 v72, 0xffff0000, v247
	v_and_b32_e32 v73, 0xffff0000, v243
	v_mul_f32_e32 v72, v72, v73
	v_mul_f32_e32 v73, 0xbfb8aa3b, v75
	v_exp_f32_e32 v73, v73
	v_add_f32_e32 v69, 1.0, v69
	v_exp_f32_e32 v71, v71
	v_rcp_f32_e32 v69, v69
	v_add_f32_e32 v73, 1.0, v73
	v_rcp_f32_e32 v73, v73
	v_mul_f32_e32 v64, 0xbfb8aa3b, v64
	v_add_f32_e32 v70, 1.0, v70
	v_exp_f32_e32 v64, v64
	v_mul_f32_e32 v75, v73, v72
	v_cvt_pk_bf16_f32 v72, v76, v77
	v_lshl_add_u64 v[76:77], s[18:19], 0, v[154:155]
	v_cvt_pk_bf16_f32 v73, v78, v79
	v_lshl_add_u64 v[112:113], v[76:77], 0, v[190:191]
	v_cvt_pk_bf16_f32 v74, v80, v81
	v_cvt_pk_bf16_f32 v75, v82, v75
	global_store_dwordx4 v[112:113], v[72:75], off
	v_rcp_f32_e32 v70, v70
	v_mul_f32_e32 v65, 0xbfb8aa3b, v65
	v_lshlrev_b32_e32 v72, 16, v252
	s_nop 0
	v_lshlrev_b32_e32 v73, 16, v248
	v_mul_f32_e32 v72, v72, v73
	v_mul_f32_e32 v68, v68, v72
	v_and_b32_e32 v72, 0xffff0000, v252
	v_and_b32_e32 v73, 0xffff0000, v248
	v_mul_f32_e32 v72, v72, v73
	v_add_f32_e32 v71, 1.0, v71
	v_exp_f32_e32 v65, v65
	v_mul_f32_e32 v69, v69, v72
	v_lshlrev_b32_e32 v72, 16, v253
	v_lshlrev_b32_e32 v73, 16, v249
	v_rcp_f32_e32 v71, v71
	v_mul_f32_e32 v72, v72, v73
	v_add_f32_e32 v64, 1.0, v64
	v_mul_f32_e32 v70, v70, v72
	v_and_b32_e32 v72, 0xffff0000, v253
	v_and_b32_e32 v73, 0xffff0000, v249
	v_rcp_f32_e32 v64, v64
	v_mul_f32_e32 v72, v72, v73
	v_add_f32_e32 v65, 1.0, v65
	v_mul_f32_e32 v71, v71, v72
	v_lshlrev_b32_e32 v72, 16, v254
	v_lshlrev_b32_e32 v73, 16, v250
	v_rcp_f32_e32 v65, v65
	v_mul_f32_e32 v72, v72, v73
	v_mul_f32_e32 v72, v64, v72
	v_and_b32_e32 v64, 0xffff0000, v254
	v_and_b32_e32 v73, 0xffff0000, v250
	v_mul_f32_e32 v64, v64, v73
	v_pk_add_f32 v[66:67], v[66:67], v[90:91]
	v_mul_f32_e32 v73, v65, v64
	v_lshlrev_b32_e32 v64, 16, v255
	v_lshlrev_b32_e32 v65, 16, v251
	v_mul_f32_e32 v64, v64, v65
	v_mul_f32_e32 v65, 0xbfb8aa3b, v66
	v_exp_f32_e32 v65, v65
	v_mov_b64_e32 v[108:109], s[20:21]
	v_lshl_add_u64 v[76:77], s[36:37], 0, v[204:205]
	v_add_f32_e32 v65, 1.0, v65
	v_rcp_f32_e32 v65, v65
	s_nop 0
	v_mul_f32_e32 v74, v65, v64
	v_and_b32_e32 v64, 0xffff0000, v255
	v_and_b32_e32 v65, 0xffff0000, v251
	v_mul_f32_e32 v64, v64, v65
	v_mul_f32_e32 v65, 0xbfb8aa3b, v67
	v_exp_f32_e32 v65, v65
	s_nop 0
	v_add_f32_e32 v65, 1.0, v65
	v_rcp_f32_e32 v65, v65
	s_nop 0
	v_mul_f32_e32 v67, v65, v64
	v_cvt_pk_bf16_f32 v64, v68, v69
	v_lshl_add_u64 v[68:69], s[18:19], 0, v[158:159]
	v_lshl_add_u64 v[104:105], v[68:69], 0, v[190:191]
	v_cvt_pk_bf16_f32 v65, v70, v71
	v_cvt_pk_bf16_f32 v66, v72, v73
	v_cvt_pk_bf16_f32 v67, v74, v67
	global_store_dwordx4 v[104:105], v[64:67], off
	global_load_dwordx4 v[64:67], v[188:189], off offset:528
	s_nop 0
	global_load_dwordx4 v[68:71], v[188:189], off offset:512
	v_or_b32_e32 v72, 0x80, v186
	v_ashrrev_i32_e32 v73, 31, v72
	v_mad_i64_i32 v[74:75], s[4:5], v184, s67, v[108:109]
	v_lshlrev_b64 v[106:107], 1, v[72:73]
	v_lshl_add_u64 v[72:73], v[74:75], 0, v[106:107]
	v_lshl_add_u64 v[76:77], v[76:77], 0, v[106:107]
	global_load_dwordx4 v[96:99], v[72:73], off nt
	s_waitcnt vmcnt(2)
	v_pk_add_f32 v[56:57], v[56:57], v[64:65]
	global_load_dwordx4 v[76:79], v[76:77], off nt
	v_lshl_add_u64 v[72:73], s[36:37], 0, v[192:193]
	v_lshl_add_u64 v[72:73], v[72:73], 0, v[106:107]
	global_load_dwordx4 v[100:103], v[72:73], off nt
	v_mad_i64_i32 v[72:73], s[4:5], v196, s67, v[108:109]
	v_lshl_add_u64 v[72:73], v[72:73], 0, v[106:107]
	global_load_dwordx4 v[88:91], v[72:73], off nt
	v_lshl_add_u64 v[72:73], s[36:37], 0, v[194:195]
	v_lshl_add_u64 v[72:73], v[72:73], 0, v[106:107]
	global_load_dwordx4 v[92:95], v[72:73], off nt
	v_mad_i64_i32 v[72:73], s[4:5], v200, s67, v[108:109]
	v_lshl_add_u64 v[72:73], v[72:73], 0, v[106:107]
	global_load_dwordx4 v[80:83], v[72:73], off nt
	v_lshl_add_u64 v[72:73], s[36:37], 0, v[198:199]
	v_lshl_add_u64 v[72:73], v[72:73], 0, v[106:107]
	global_load_dwordx4 v[84:87], v[72:73], off nt
	s_waitcnt vmcnt(7)
	v_pk_add_f32 v[60:61], v[60:61], v[68:69]
	v_pk_add_f32 v[62:63], v[62:63], v[70:71]
	v_mul_f32_e32 v61, 0xbfb8aa3b, v61
	v_exp_f32_e32 v61, v61
	v_mul_f32_e32 v62, 0xbfb8aa3b, v62
	v_exp_f32_e32 v62, v62
	v_mul_f32_e32 v63, 0xbfb8aa3b, v63
	v_add_f32_e32 v61, 1.0, v61
	v_exp_f32_e32 v63, v63
	v_rcp_f32_e32 v61, v61
	v_mul_f32_e32 v56, 0xbfb8aa3b, v56
	v_add_f32_e32 v62, 1.0, v62
	v_exp_f32_e32 v56, v56
	s_waitcnt vmcnt(6)
	v_lshlrev_b32_e32 v111, 16, v96
	v_and_b32_e32 v96, 0xffff0000, v96
	v_rcp_f32_e32 v62, v62
	v_mul_f32_e32 v57, 0xbfb8aa3b, v57
	v_add_f32_e32 v63, 1.0, v63
	v_exp_f32_e32 v57, v57
	v_rcp_f32_e32 v63, v63
	v_add_f32_e32 v56, 1.0, v56
	v_rcp_f32_e32 v56, v56
	v_add_f32_e32 v57, 1.0, v57
	v_rcp_f32_e32 v57, v57
	v_pk_add_f32 v[58:59], v[58:59], v[66:67]
	v_mad_i64_i32 v[72:73], s[4:5], v202, s67, v[108:109]
	v_lshl_add_u64 v[72:73], v[72:73], 0, v[106:107]
	v_mul_f32_e32 v60, 0xbfb8aa3b, v60
	global_load_dwordx4 v[72:75], v[72:73], off nt
	v_add_u32_e32 v230, 0x80, v184
	v_mad_i64_i32 v[238:239], s[98:99], v230, s67, v[208:209]
	global_load_dwordx4 v[218:221], v[238:239], off offset:256 nt
	v_ashrrev_i32_e32 v231, 31, v230
	v_lshlrev_b64 v[230:231], 12, v[230:231]
	v_lshl_add_u64 v[230:231], v[206:207], 0, v[230:231]
	global_load_dwordx4 v[222:225], v[230:231], off offset:256 nt
	v_add_u32_e32 v230, 0x90, v184
	v_mad_i64_i32 v[238:239], s[98:99], v230, s67, v[208:209]
	global_load_dwordx4 v[226:229], v[238:239], off offset:256 nt
	v_ashrrev_i32_e32 v231, 31, v230
	v_lshlrev_b64 v[230:231], 12, v[230:231]
	v_lshl_add_u64 v[230:231], v[206:207], 0, v[230:231]
	global_load_dwordx4 v[234:237], v[230:231], off offset:256 nt
	v_add_u32_e32 v230, 0xa0, v184
	v_mad_i64_i32 v[238:239], s[98:99], v230, s67, v[208:209]
	global_load_dwordx4 v[240:243], v[238:239], off offset:256 nt
	v_ashrrev_i32_e32 v231, 31, v230
	v_lshlrev_b64 v[230:231], 12, v[230:231]
	v_lshl_add_u64 v[230:231], v[206:207], 0, v[230:231]
	global_load_dwordx4 v[244:247], v[230:231], off offset:256 nt
	v_add_u32_e32 v230, 0xb0, v184
	v_mad_i64_i32 v[238:239], s[98:99], v230, s67, v[208:209]
	global_load_dwordx4 v[248:251], v[238:239], off offset:256 nt
	v_ashrrev_i32_e32 v231, 31, v230
	v_lshlrev_b64 v[230:231], 12, v[230:231]
	v_lshl_add_u64 v[230:231], v[206:207], 0, v[230:231]
	global_load_dwordx4 v[252:255], v[230:231], off offset:256 nt
	v_exp_f32_e32 v60, v60
	v_pk_add_f32 v[52:53], v[52:53], v[68:69]
	v_pk_add_f32 v[54:55], v[54:55], v[70:71]
	v_mul_f32_e32 v52, 0xbfb8aa3b, v52
	v_exp_f32_e32 v52, v52
	v_add_f32_e32 v60, 1.0, v60
	v_mul_f32_e32 v53, 0xbfb8aa3b, v53
	v_rcp_f32_e32 v60, v60
	v_exp_f32_e32 v53, v53
	v_mul_f32_e32 v54, 0xbfb8aa3b, v54
	v_add_f32_e32 v52, 1.0, v52
	v_exp_f32_e32 v54, v54
	v_rcp_f32_e32 v52, v52
	v_mul_f32_e32 v55, 0xbfb8aa3b, v55
	v_pk_add_f32 v[48:49], v[48:49], v[64:65]
	v_add_f32_e32 v53, 1.0, v53
	v_exp_f32_e32 v55, v55
	v_rcp_f32_e32 v53, v53
	v_mul_f32_e32 v48, 0xbfb8aa3b, v48
	v_add_f32_e32 v54, 1.0, v54
	v_exp_f32_e32 v48, v48
	v_rcp_f32_e32 v54, v54
	v_mul_f32_e32 v49, 0xbfb8aa3b, v49
	v_add_f32_e32 v55, 1.0, v55
	v_exp_f32_e32 v49, v49
	v_rcp_f32_e32 v55, v55
	v_add_f32_e32 v48, 1.0, v48
	v_rcp_f32_e32 v48, v48
	v_add_f32_e32 v49, 1.0, v49
	v_rcp_f32_e32 v49, v49
	v_pk_add_f32 v[50:51], v[50:51], v[66:67]
	v_pk_add_f32 v[44:45], v[44:45], v[68:69]
	v_pk_add_f32 v[46:47], v[46:47], v[70:71]
	v_mul_f32_e32 v44, 0xbfb8aa3b, v44
	v_exp_f32_e32 v44, v44
	s_waitcnt vmcnt(13)
	v_lshlrev_b32_e32 v110, 16, v100
	v_and_b32_e32 v100, 0xffff0000, v100
	v_mul_f32_e32 v96, v100, v96
	v_mul_f32_e32 v61, v61, v96
	v_lshlrev_b32_e32 v96, 16, v101
	v_lshlrev_b32_e32 v100, 16, v97
	v_mul_f32_e32 v96, v96, v100
	v_mul_f32_e32 v62, v62, v96
	v_and_b32_e32 v96, 0xffff0000, v101
	v_and_b32_e32 v97, 0xffff0000, v97
	v_mul_f32_e32 v96, v96, v97
	v_mul_f32_e32 v63, v63, v96
	v_lshlrev_b32_e32 v96, 16, v102
	v_lshlrev_b32_e32 v97, 16, v98
	v_mul_f32_e32 v96, v96, v97
	v_mul_f32_e32 v96, v96, v56
	v_and_b32_e32 v56, 0xffff0000, v102
	v_and_b32_e32 v97, 0xffff0000, v98
	v_mul_f32_e32 v56, v56, v97
	v_mul_f32_e32 v97, v56, v57
	v_lshlrev_b32_e32 v56, 16, v103
	v_lshlrev_b32_e32 v57, 16, v99
	v_mul_f32_e32 v56, v56, v57
	v_mul_f32_e32 v57, 0xbfb8aa3b, v58
	v_exp_f32_e32 v57, v57
	v_mul_f32_e32 v110, v110, v111
	v_mul_f32_e32 v60, v60, v110
	v_mul_f32_e32 v45, 0xbfb8aa3b, v45
	v_add_f32_e32 v57, 1.0, v57
	v_rcp_f32_e32 v57, v57
	v_exp_f32_e32 v45, v45
	v_mul_f32_e32 v46, 0xbfb8aa3b, v46
	v_add_f32_e32 v44, 1.0, v44
	v_mul_f32_e32 v98, v56, v57
	v_and_b32_e32 v56, 0xffff0000, v103
	v_and_b32_e32 v57, 0xffff0000, v99
	v_mul_f32_e32 v56, v56, v57
	v_mul_f32_e32 v57, 0xbfb8aa3b, v59
	v_exp_f32_e32 v57, v57
	v_exp_f32_e32 v46, v46
	v_rcp_f32_e32 v44, v44
	v_mul_f32_e32 v47, 0xbfb8aa3b, v47
	v_add_f32_e32 v57, 1.0, v57
	v_rcp_f32_e32 v57, v57
	v_pk_add_f32 v[40:41], v[40:41], v[64:65]
	v_add_f32_e32 v45, 1.0, v45
	v_exp_f32_e32 v47, v47
	v_mul_f32_e32 v59, v56, v57
	v_cvt_pk_bf16_f32 v56, v60, v61
	v_cvt_pk_bf16_f32 v57, v62, v63
	v_cvt_pk_bf16_f32 v58, v96, v97
	v_cvt_pk_bf16_f32 v59, v98, v59
	global_store_dwordx4 v[144:145], v[56:59], off offset:256
	v_rcp_f32_e32 v45, v45
	v_mul_f32_e32 v40, 0xbfb8aa3b, v40
	s_waitcnt vmcnt(12)
	v_lshlrev_b32_e32 v56, 16, v92
	v_lshlrev_b32_e32 v57, 16, v88
	v_mul_f32_e32 v56, v56, v57
	v_mul_f32_e32 v52, v52, v56
	v_and_b32_e32 v56, 0xffff0000, v92
	v_and_b32_e32 v57, 0xffff0000, v88
	v_mul_f32_e32 v56, v56, v57
	v_mul_f32_e32 v53, v53, v56
	v_lshlrev_b32_e32 v56, 16, v93
	v_lshlrev_b32_e32 v57, 16, v89
	v_mul_f32_e32 v56, v56, v57
	v_mul_f32_e32 v54, v54, v56
	v_and_b32_e32 v56, 0xffff0000, v93
	v_and_b32_e32 v57, 0xffff0000, v89
	v_mul_f32_e32 v56, v56, v57
	v_mul_f32_e32 v55, v55, v56
	v_lshlrev_b32_e32 v56, 16, v94
	v_lshlrev_b32_e32 v57, 16, v90
	v_mul_f32_e32 v56, v56, v57
	v_mul_f32_e32 v56, v48, v56
	v_and_b32_e32 v48, 0xffff0000, v94
	v_and_b32_e32 v57, 0xffff0000, v90
	v_mul_f32_e32 v48, v48, v57
	v_mul_f32_e32 v57, v49, v48
	v_lshlrev_b32_e32 v48, 16, v95
	v_lshlrev_b32_e32 v49, 16, v91
	v_mul_f32_e32 v48, v48, v49
	v_mul_f32_e32 v49, 0xbfb8aa3b, v50
	v_exp_f32_e32 v49, v49
	v_add_f32_e32 v46, 1.0, v46
	v_exp_f32_e32 v40, v40
	v_rcp_f32_e32 v46, v46
	v_add_f32_e32 v49, 1.0, v49
	v_rcp_f32_e32 v49, v49
	v_mul_f32_e32 v41, 0xbfb8aa3b, v41
	v_add_f32_e32 v47, 1.0, v47
	v_exp_f32_e32 v41, v41
	v_mul_f32_e32 v58, v49, v48
	v_and_b32_e32 v48, 0xffff0000, v95
	v_and_b32_e32 v49, 0xffff0000, v91
	v_mul_f32_e32 v48, v48, v49
	v_mul_f32_e32 v49, 0xbfb8aa3b, v51
	v_exp_f32_e32 v49, v49
	v_rcp_f32_e32 v47, v47
	v_add_f32_e32 v40, 1.0, v40
	v_rcp_f32_e32 v40, v40
	v_add_f32_e32 v49, 1.0, v49
	v_rcp_f32_e32 v49, v49
	v_add_f32_e32 v41, 1.0, v41
	v_rcp_f32_e32 v41, v41
	v_pk_add_f32 v[42:43], v[42:43], v[66:67]
	v_mul_f32_e32 v51, v49, v48
	v_cvt_pk_bf16_f32 v48, v52, v53
	v_cvt_pk_bf16_f32 v49, v54, v55
	v_cvt_pk_bf16_f32 v50, v56, v57
	v_cvt_pk_bf16_f32 v51, v58, v51
	global_store_dwordx4 v[146:147], v[48:51], off offset:256
	v_pk_add_f32 v[36:37], v[36:37], v[68:69]
	v_pk_add_f32 v[38:39], v[38:39], v[70:71]
	s_waitcnt vmcnt(11)
	v_lshlrev_b32_e32 v48, 16, v84
	v_lshlrev_b32_e32 v49, 16, v80
	v_mul_f32_e32 v48, v48, v49
	v_mul_f32_e32 v44, v44, v48
	v_and_b32_e32 v48, 0xffff0000, v84
	v_and_b32_e32 v49, 0xffff0000, v80
	v_mul_f32_e32 v48, v48, v49
	v_mul_f32_e32 v45, v45, v48
	v_lshlrev_b32_e32 v48, 16, v85
	v_lshlrev_b32_e32 v49, 16, v81
	v_mul_f32_e32 v48, v48, v49
	v_mul_f32_e32 v46, v46, v48
	v_and_b32_e32 v48, 0xffff0000, v85
	v_and_b32_e32 v49, 0xffff0000, v81
	v_mul_f32_e32 v48, v48, v49
	v_mul_f32_e32 v47, v47, v48
	v_lshlrev_b32_e32 v48, 16, v86
	v_lshlrev_b32_e32 v49, 16, v82
	v_mul_f32_e32 v48, v48, v49
	v_mul_f32_e32 v48, v40, v48
	v_and_b32_e32 v40, 0xffff0000, v86
	v_and_b32_e32 v49, 0xffff0000, v82
	v_mul_f32_e32 v40, v40, v49
	v_mul_f32_e32 v49, v41, v40
	v_lshlrev_b32_e32 v40, 16, v87
	v_lshlrev_b32_e32 v41, 16, v83
	v_mul_f32_e32 v40, v40, v41
	v_mul_f32_e32 v41, 0xbfb8aa3b, v42
	v_exp_f32_e32 v41, v41
	v_mul_f32_e32 v36, 0xbfb8aa3b, v36
	v_exp_f32_e32 v36, v36
	v_mul_f32_e32 v37, 0xbfb8aa3b, v37
	v_add_f32_e32 v41, 1.0, v41
	v_rcp_f32_e32 v41, v41
	v_exp_f32_e32 v37, v37
	v_mul_f32_e32 v38, 0xbfb8aa3b, v38
	v_add_f32_e32 v36, 1.0, v36
	v_mul_f32_e32 v50, v41, v40
	v_and_b32_e32 v40, 0xffff0000, v87
	v_and_b32_e32 v41, 0xffff0000, v83
	v_mul_f32_e32 v40, v40, v41
	v_mul_f32_e32 v41, 0xbfb8aa3b, v43
	v_exp_f32_e32 v41, v41
	v_exp_f32_e32 v38, v38
	v_rcp_f32_e32 v36, v36
	v_mul_f32_e32 v39, 0xbfb8aa3b, v39
	v_add_f32_e32 v41, 1.0, v41
	v_rcp_f32_e32 v41, v41
	v_pk_add_f32 v[32:33], v[32:33], v[64:65]
	v_add_f32_e32 v37, 1.0, v37
	v_exp_f32_e32 v39, v39
	v_mul_f32_e32 v43, v41, v40
	v_cvt_pk_bf16_f32 v40, v44, v45
	v_cvt_pk_bf16_f32 v41, v46, v47
	v_cvt_pk_bf16_f32 v42, v48, v49
	v_cvt_pk_bf16_f32 v43, v50, v43
	global_store_dwordx4 v[136:137], v[40:43], off offset:256
	v_rcp_f32_e32 v37, v37
	v_mul_f32_e32 v32, 0xbfb8aa3b, v32
	v_lshlrev_b32_e32 v40, 16, v76
	s_waitcnt vmcnt(11)
	v_lshlrev_b32_e32 v41, 16, v72
	v_mul_f32_e32 v40, v40, v41
	v_add_f32_e32 v38, 1.0, v38
	v_exp_f32_e32 v32, v32
	v_mul_f32_e32 v36, v36, v40
	v_and_b32_e32 v40, 0xffff0000, v76
	v_and_b32_e32 v41, 0xffff0000, v72
	v_rcp_f32_e32 v38, v38
	v_mul_f32_e32 v33, 0xbfb8aa3b, v33
	v_mul_f32_e32 v40, v40, v41
	v_add_f32_e32 v39, 1.0, v39
	v_exp_f32_e32 v33, v33
	v_mul_f32_e32 v37, v37, v40
	v_lshlrev_b32_e32 v40, 16, v77
	v_lshlrev_b32_e32 v41, 16, v73
	v_rcp_f32_e32 v39, v39
	v_mul_f32_e32 v40, v40, v41
	v_add_f32_e32 v32, 1.0, v32
	v_mul_f32_e32 v38, v38, v40
	v_and_b32_e32 v40, 0xffff0000, v77
	v_and_b32_e32 v41, 0xffff0000, v73
	v_rcp_f32_e32 v32, v32
	v_mul_f32_e32 v40, v40, v41
	v_add_f32_e32 v33, 1.0, v33
	v_mul_f32_e32 v39, v39, v40
	v_lshlrev_b32_e32 v40, 16, v78
	v_lshlrev_b32_e32 v41, 16, v74
	v_rcp_f32_e32 v33, v33
	v_mul_f32_e32 v40, v40, v41
	v_mul_f32_e32 v40, v32, v40
	v_and_b32_e32 v32, 0xffff0000, v78
	v_and_b32_e32 v41, 0xffff0000, v74
	v_mul_f32_e32 v32, v32, v41
	v_pk_add_f32 v[34:35], v[34:35], v[66:67]
	v_mul_f32_e32 v41, v33, v32
	v_lshlrev_b32_e32 v32, 16, v79
	v_lshlrev_b32_e32 v33, 16, v75
	v_mul_f32_e32 v32, v32, v33
	v_mul_f32_e32 v33, 0xbfb8aa3b, v34
	v_exp_f32_e32 v33, v33
	v_pk_add_f32 v[28:29], v[28:29], v[68:69]
	v_pk_add_f32 v[30:31], v[30:31], v[70:71]
	v_mul_f32_e32 v29, 0xbfb8aa3b, v29
	v_add_f32_e32 v33, 1.0, v33
	v_rcp_f32_e32 v33, v33
	v_exp_f32_e32 v29, v29
	v_mul_f32_e32 v30, 0xbfb8aa3b, v30
	v_exp_f32_e32 v30, v30
	v_mul_f32_e32 v42, v33, v32
	v_and_b32_e32 v32, 0xffff0000, v79
	v_and_b32_e32 v33, 0xffff0000, v75
	v_mul_f32_e32 v32, v32, v33
	v_mul_f32_e32 v33, 0xbfb8aa3b, v35
	v_exp_f32_e32 v33, v33
	v_mul_f32_e32 v31, 0xbfb8aa3b, v31
	v_pk_add_f32 v[24:25], v[24:25], v[64:65]
	v_add_f32_e32 v29, 1.0, v29
	v_add_f32_e32 v33, 1.0, v33
	v_rcp_f32_e32 v33, v33
	v_exp_f32_e32 v31, v31
	v_rcp_f32_e32 v29, v29
	v_mul_f32_e32 v24, 0xbfb8aa3b, v24
	v_mul_f32_e32 v35, v33, v32
	v_cvt_pk_bf16_f32 v32, v36, v37
	v_cvt_pk_bf16_f32 v33, v38, v39
	v_cvt_pk_bf16_f32 v34, v40, v41
	v_cvt_pk_bf16_f32 v35, v42, v35
	global_store_dwordx4 v[138:139], v[32:35], off offset:256
	v_lshl_add_u64 v[36:37], s[36:37], 0, v[158:159]
	v_lshl_add_u64 v[36:37], v[36:37], 0, v[106:107]
	v_mad_i64_i32 v[32:33], s[4:5], v140, s67, v[108:109]
	v_lshl_add_u64 v[32:33], v[32:33], 0, v[106:107]
	s_nop 0
	v_add_f32_e32 v30, 1.0, v30
	s_nop 0
	v_lshl_add_u64 v[32:33], s[36:37], 0, v[142:143]
	v_lshl_add_u64 v[32:33], v[32:33], 0, v[106:107]
	s_nop 0
	v_mad_i64_i32 v[32:33], s[4:5], v148, s67, v[108:109]
	v_lshl_add_u64 v[32:33], v[32:33], 0, v[106:107]
	s_nop 0
	v_lshl_add_u64 v[32:33], s[36:37], 0, v[150:151]
	v_lshl_add_u64 v[32:33], v[32:33], 0, v[106:107]
	s_nop 0
	v_mad_i64_i32 v[32:33], s[4:5], v152, s67, v[108:109]
	v_lshl_add_u64 v[32:33], v[32:33], 0, v[106:107]
	s_nop 0
	v_lshl_add_u64 v[32:33], s[36:37], 0, v[154:155]
	v_lshl_add_u64 v[32:33], v[32:33], 0, v[106:107]
	s_nop 0
	v_exp_f32_e32 v24, v24
	v_rcp_f32_e32 v30, v30
	v_mul_f32_e32 v25, 0xbfb8aa3b, v25
	v_add_f32_e32 v31, 1.0, v31
	v_exp_f32_e32 v25, v25
	v_rcp_f32_e32 v31, v31
	v_add_f32_e32 v24, 1.0, v24
	v_rcp_f32_e32 v24, v24
	v_add_f32_e32 v25, 1.0, v25
	v_rcp_f32_e32 v25, v25
	v_pk_add_f32 v[26:27], v[26:27], v[66:67]
	v_mad_i64_i32 v[32:33], s[4:5], v156, s67, v[108:109]
	v_lshl_add_u64 v[32:33], v[32:33], 0, v[106:107]
	v_mul_f32_e32 v28, 0xbfb8aa3b, v28
	s_nop 0
	v_exp_f32_e32 v28, v28
	v_pk_add_f32 v[20:21], v[20:21], v[68:69]
	v_pk_add_f32 v[22:23], v[22:23], v[70:71]
	v_mul_f32_e32 v20, 0xbfb8aa3b, v20
	v_exp_f32_e32 v20, v20
	v_add_f32_e32 v28, 1.0, v28
	v_mul_f32_e32 v21, 0xbfb8aa3b, v21
	v_rcp_f32_e32 v28, v28
	v_exp_f32_e32 v21, v21
	v_mul_f32_e32 v22, 0xbfb8aa3b, v22
	v_add_f32_e32 v20, 1.0, v20
	v_exp_f32_e32 v22, v22
	v_rcp_f32_e32 v20, v20
	v_mul_f32_e32 v23, 0xbfb8aa3b, v23
	v_pk_add_f32 v[16:17], v[16:17], v[64:65]
	v_add_f32_e32 v21, 1.0, v21
	v_exp_f32_e32 v23, v23
	v_rcp_f32_e32 v21, v21
	v_mul_f32_e32 v16, 0xbfb8aa3b, v16
	v_add_f32_e32 v22, 1.0, v22
	v_exp_f32_e32 v16, v16
	v_rcp_f32_e32 v22, v22
	v_mul_f32_e32 v17, 0xbfb8aa3b, v17
	v_add_f32_e32 v23, 1.0, v23
	v_exp_f32_e32 v17, v17
	v_rcp_f32_e32 v23, v23
	v_add_f32_e32 v16, 1.0, v16
	v_rcp_f32_e32 v16, v16
	v_add_f32_e32 v17, 1.0, v17
	v_rcp_f32_e32 v17, v17
	v_pk_add_f32 v[18:19], v[18:19], v[66:67]
	v_pk_add_f32 v[12:13], v[12:13], v[68:69]
	v_pk_add_f32 v[14:15], v[14:15], v[70:71]
	v_mul_f32_e32 v12, 0xbfb8aa3b, v12
	v_exp_f32_e32 v12, v12
	v_mul_f32_e32 v13, 0xbfb8aa3b, v13
	v_exp_f32_e32 v13, v13
	v_mul_f32_e32 v14, 0xbfb8aa3b, v14
	v_add_f32_e32 v12, 1.0, v12
	v_exp_f32_e32 v14, v14
	v_rcp_f32_e32 v12, v12
	v_mul_f32_e32 v15, 0xbfb8aa3b, v15
	v_pk_add_f32 v[8:9], v[8:9], v[64:65]
	v_add_f32_e32 v13, 1.0, v13
	s_waitcnt vmcnt(4)
	v_lshlrev_b32_e32 v73, 16, v218
	v_and_b32_e32 v56, 0xffff0000, v218
	v_exp_f32_e32 v15, v15
	v_rcp_f32_e32 v13, v13
	v_mul_f32_e32 v8, 0xbfb8aa3b, v8
	s_nop 0
	v_lshlrev_b32_e32 v72, 16, v222
	v_and_b32_e32 v60, 0xffff0000, v222
	v_mul_f32_e32 v56, v60, v56
	v_mul_f32_e32 v29, v29, v56
	v_lshlrev_b32_e32 v56, 16, v223
	v_lshlrev_b32_e32 v60, 16, v219
	v_mul_f32_e32 v56, v56, v60
	v_mul_f32_e32 v30, v30, v56
	v_and_b32_e32 v56, 0xffff0000, v223
	v_and_b32_e32 v57, 0xffff0000, v219
	v_mul_f32_e32 v56, v56, v57
	v_mul_f32_e32 v31, v31, v56
	v_lshlrev_b32_e32 v56, 16, v224
	v_lshlrev_b32_e32 v57, 16, v220
	v_mul_f32_e32 v56, v56, v57
	v_mul_f32_e32 v56, v24, v56
	v_and_b32_e32 v24, 0xffff0000, v224
	v_and_b32_e32 v57, 0xffff0000, v220
	v_mul_f32_e32 v24, v24, v57
	v_mul_f32_e32 v57, v25, v24
	v_lshlrev_b32_e32 v24, 16, v225
	v_lshlrev_b32_e32 v25, 16, v221
	v_mul_f32_e32 v24, v24, v25
	v_mul_f32_e32 v25, 0xbfb8aa3b, v26
	v_exp_f32_e32 v25, v25
	v_mul_f32_e32 v72, v72, v73
	v_mul_f32_e32 v28, v28, v72
	v_add_f32_e32 v14, 1.0, v14
	v_add_f32_e32 v25, 1.0, v25
	v_rcp_f32_e32 v25, v25
	v_exp_f32_e32 v8, v8
	v_rcp_f32_e32 v14, v14
	v_mul_f32_e32 v9, 0xbfb8aa3b, v9
	v_mul_f32_e32 v58, v25, v24
	v_and_b32_e32 v24, 0xffff0000, v225
	v_and_b32_e32 v25, 0xffff0000, v221
	v_mul_f32_e32 v24, v24, v25
	v_mul_f32_e32 v25, 0xbfb8aa3b, v27
	v_exp_f32_e32 v25, v25
	v_add_f32_e32 v15, 1.0, v15
	v_exp_f32_e32 v9, v9
	v_rcp_f32_e32 v15, v15
	v_add_f32_e32 v25, 1.0, v25
	v_rcp_f32_e32 v25, v25
	v_add_f32_e32 v8, 1.0, v8
	v_rcp_f32_e32 v8, v8
	v_add_f32_e32 v9, 1.0, v9
	v_mul_f32_e32 v27, v25, v24
	v_cvt_pk_bf16_f32 v24, v28, v29
	v_cvt_pk_bf16_f32 v25, v30, v31
	v_cvt_pk_bf16_f32 v26, v56, v57
	v_cvt_pk_bf16_f32 v27, v58, v27
	global_store_dwordx4 v[128:129], v[24:27], off offset:256
	v_rcp_f32_e32 v9, v9
	v_pk_add_f32 v[10:11], v[10:11], v[66:67]
	s_nop 0
	v_lshlrev_b32_e32 v24, 16, v234
	v_lshlrev_b32_e32 v25, 16, v226
	v_mul_f32_e32 v24, v24, v25
	v_mul_f32_e32 v20, v20, v24
	v_and_b32_e32 v24, 0xffff0000, v234
	v_and_b32_e32 v25, 0xffff0000, v226
	v_mul_f32_e32 v24, v24, v25
	v_mul_f32_e32 v21, v21, v24
	v_lshlrev_b32_e32 v24, 16, v235
	v_lshlrev_b32_e32 v25, 16, v227
	v_mul_f32_e32 v24, v24, v25
	v_mul_f32_e32 v22, v22, v24
	v_and_b32_e32 v24, 0xffff0000, v235
	v_and_b32_e32 v25, 0xffff0000, v227
	v_mul_f32_e32 v24, v24, v25
	v_mul_f32_e32 v23, v23, v24
	v_lshlrev_b32_e32 v24, 16, v236
	v_lshlrev_b32_e32 v25, 16, v228
	v_mul_f32_e32 v24, v24, v25
	v_mul_f32_e32 v24, v16, v24
	v_and_b32_e32 v16, 0xffff0000, v236
	v_and_b32_e32 v25, 0xffff0000, v228
	v_mul_f32_e32 v16, v16, v25
	v_mul_f32_e32 v25, v17, v16
	v_lshlrev_b32_e32 v16, 16, v237
	v_lshlrev_b32_e32 v17, 16, v229
	v_mul_f32_e32 v16, v16, v17
	v_mul_f32_e32 v17, 0xbfb8aa3b, v18
	v_exp_f32_e32 v17, v17
	v_pk_add_f32 v[4:5], v[4:5], v[68:69]
	v_pk_add_f32 v[6:7], v[6:7], v[70:71]
	v_mul_f32_e32 v4, 0xbfb8aa3b, v4
	v_add_f32_e32 v17, 1.0, v17
	v_rcp_f32_e32 v17, v17
	v_exp_f32_e32 v4, v4
	v_mul_f32_e32 v5, 0xbfb8aa3b, v5
	v_exp_f32_e32 v5, v5
	v_mul_f32_e32 v26, v17, v16
	v_and_b32_e32 v16, 0xffff0000, v237
	v_and_b32_e32 v17, 0xffff0000, v229
	v_mul_f32_e32 v16, v16, v17
	v_mul_f32_e32 v17, 0xbfb8aa3b, v19
	v_exp_f32_e32 v17, v17
	v_mul_f32_e32 v6, 0xbfb8aa3b, v6
	v_add_f32_e32 v4, 1.0, v4
	v_exp_f32_e32 v6, v6
	v_add_f32_e32 v17, 1.0, v17
	v_rcp_f32_e32 v17, v17
	v_rcp_f32_e32 v4, v4
	v_mul_f32_e32 v7, 0xbfb8aa3b, v7
	v_pk_add_f32 v[0:1], v[0:1], v[64:65]
	v_mul_f32_e32 v19, v17, v16
	v_cvt_pk_bf16_f32 v16, v20, v21
	v_cvt_pk_bf16_f32 v17, v22, v23
	v_cvt_pk_bf16_f32 v18, v24, v25
	v_cvt_pk_bf16_f32 v19, v26, v19
	global_store_dwordx4 v[120:121], v[16:19], off offset:256
	v_add_f32_e32 v5, 1.0, v5
	v_exp_f32_e32 v7, v7
	s_nop 0
	v_lshlrev_b32_e32 v16, 16, v244
	v_lshlrev_b32_e32 v17, 16, v240
	v_mul_f32_e32 v16, v16, v17
	v_mul_f32_e32 v12, v12, v16
	v_and_b32_e32 v16, 0xffff0000, v244
	v_and_b32_e32 v17, 0xffff0000, v240
	v_mul_f32_e32 v16, v16, v17
	v_mul_f32_e32 v13, v13, v16
	v_lshlrev_b32_e32 v16, 16, v245
	v_lshlrev_b32_e32 v17, 16, v241
	v_mul_f32_e32 v16, v16, v17
	v_mul_f32_e32 v14, v14, v16
	v_and_b32_e32 v16, 0xffff0000, v245
	v_and_b32_e32 v17, 0xffff0000, v241
	v_mul_f32_e32 v16, v16, v17
	v_mul_f32_e32 v15, v15, v16
	v_lshlrev_b32_e32 v16, 16, v246
	v_lshlrev_b32_e32 v17, 16, v242
	v_mul_f32_e32 v16, v16, v17
	v_mul_f32_e32 v16, v8, v16
	v_and_b32_e32 v8, 0xffff0000, v246
	v_and_b32_e32 v17, 0xffff0000, v242
	v_mul_f32_e32 v8, v8, v17
	v_mul_f32_e32 v17, v9, v8
	v_lshlrev_b32_e32 v8, 16, v247
	v_lshlrev_b32_e32 v9, 16, v243
	v_mul_f32_e32 v8, v8, v9
	v_mul_f32_e32 v9, 0xbfb8aa3b, v10
	v_exp_f32_e32 v9, v9
	v_rcp_f32_e32 v5, v5
	v_mul_f32_e32 v0, 0xbfb8aa3b, v0
	v_add_f32_e32 v6, 1.0, v6
	v_add_f32_e32 v9, 1.0, v9
	v_rcp_f32_e32 v9, v9
	v_exp_f32_e32 v0, v0
	v_rcp_f32_e32 v6, v6
	v_mul_f32_e32 v1, 0xbfb8aa3b, v1
	v_mul_f32_e32 v18, v9, v8
	v_and_b32_e32 v8, 0xffff0000, v247
	v_and_b32_e32 v9, 0xffff0000, v243
	v_mul_f32_e32 v8, v8, v9
	v_mul_f32_e32 v9, 0xbfb8aa3b, v11
	v_exp_f32_e32 v9, v9
	v_add_f32_e32 v7, 1.0, v7
	v_exp_f32_e32 v1, v1
	v_rcp_f32_e32 v7, v7
	v_add_f32_e32 v9, 1.0, v9
	v_rcp_f32_e32 v9, v9
	v_add_f32_e32 v0, 1.0, v0
	v_rcp_f32_e32 v0, v0
	v_add_f32_e32 v1, 1.0, v1
	v_mul_f32_e32 v11, v9, v8
	v_cvt_pk_bf16_f32 v8, v12, v13
	v_cvt_pk_bf16_f32 v9, v14, v15
	v_cvt_pk_bf16_f32 v10, v16, v17
	v_cvt_pk_bf16_f32 v11, v18, v11
	global_store_dwordx4 v[112:113], v[8:11], off offset:256
	v_rcp_f32_e32 v1, v1
	v_pk_add_f32 v[2:3], v[2:3], v[66:67]
	v_lshlrev_b32_e32 v8, 16, v252
	s_nop 0
	v_lshlrev_b32_e32 v9, 16, v248
	v_mul_f32_e32 v8, v8, v9
	v_mul_f32_e32 v4, v4, v8
	v_and_b32_e32 v8, 0xffff0000, v252
	v_and_b32_e32 v9, 0xffff0000, v248
	v_mul_f32_e32 v8, v8, v9
	v_mul_f32_e32 v5, v5, v8
	v_lshlrev_b32_e32 v8, 16, v253
	v_lshlrev_b32_e32 v9, 16, v249
	v_mul_f32_e32 v8, v8, v9
	v_mul_f32_e32 v6, v6, v8
	v_and_b32_e32 v8, 0xffff0000, v253
	v_and_b32_e32 v9, 0xffff0000, v249
	v_mul_f32_e32 v8, v8, v9
	v_mul_f32_e32 v7, v7, v8
	v_lshlrev_b32_e32 v8, 16, v254
	v_lshlrev_b32_e32 v9, 16, v250
	v_mul_f32_e32 v8, v8, v9
	v_mul_f32_e32 v8, v0, v8
	v_and_b32_e32 v0, 0xffff0000, v254
	v_and_b32_e32 v9, 0xffff0000, v250
	v_mul_f32_e32 v0, v0, v9
	v_mul_f32_e32 v9, v1, v0
	v_lshlrev_b32_e32 v0, 16, v255
	v_lshlrev_b32_e32 v1, 16, v251
	v_mul_f32_e32 v0, v0, v1
	v_mul_f32_e32 v1, 0xbfb8aa3b, v2
	v_exp_f32_e32 v1, v1
	s_mov_b64 s[4:5], -1
	v_add_f32_e32 v1, 1.0, v1
	v_rcp_f32_e32 v1, v1
	s_nop 0
	v_mul_f32_e32 v10, v1, v0
	v_and_b32_e32 v0, 0xffff0000, v255
	v_and_b32_e32 v1, 0xffff0000, v251
	v_mul_f32_e32 v0, v0, v1
	v_mul_f32_e32 v1, 0xbfb8aa3b, v3
	v_exp_f32_e32 v1, v1
	s_nop 0
	v_add_f32_e32 v1, 1.0, v1
	v_rcp_f32_e32 v1, v1
	s_nop 0
	v_mul_f32_e32 v3, v1, v0
	v_cvt_pk_bf16_f32 v0, v4, v5
	v_cvt_pk_bf16_f32 v1, v6, v7
	v_cvt_pk_bf16_f32 v2, v8, v9
	v_cvt_pk_bf16_f32 v3, v10, v3
	global_store_dwordx4 v[104:105], v[0:3], off offset:256
	s_cbranch_vccnz .LBB0_391
	s_andn2_b64 vcc, exec, s[0:1]
	s_cbranch_vccnz .LBB0_390
	s_barrier
	s_branch .LBB0_390

	.amdhsa_kernel _Z8yoco_fwd6Params
		.amdhsa_group_segment_fixed_size 0
		.amdhsa_private_segment_fixed_size 0
		.amdhsa_kernarg_size 456
		.amdhsa_user_sgpr_count 2
		.amdhsa_user_sgpr_dispatch_ptr 0
		.amdhsa_user_sgpr_queue_ptr 0
		.amdhsa_user_sgpr_kernarg_segment_ptr 1
		.amdhsa_user_sgpr_dispatch_id 0
		.amdhsa_user_sgpr_kernarg_preload_length 0
		.amdhsa_user_sgpr_kernarg_preload_offset 0
		.amdhsa_user_sgpr_private_segment_size 0
		.amdhsa_uses_dynamic_stack 0
		.amdhsa_enable_private_segment 0
		.amdhsa_system_sgpr_workgroup_id_x 1
		.amdhsa_system_sgpr_workgroup_id_y 0
		.amdhsa_system_sgpr_workgroup_id_z 0
		.amdhsa_system_sgpr_workgroup_info 0
		.amdhsa_system_vgpr_workitem_id 2
		.amdhsa_next_free_vgpr 256
		.amdhsa_next_free_sgpr 102
		.amdhsa_accum_offset 256
		.amdhsa_reserve_vcc 1
		.amdhsa_float_round_mode_32 0
		.amdhsa_float_round_mode_16_64 0
		.amdhsa_float_denorm_mode_32 3
		.amdhsa_float_denorm_mode_16_64 3
		.amdhsa_dx10_clamp 1
		.amdhsa_ieee_mode 1
		.amdhsa_fp16_overflow 0
		.amdhsa_tg_split 0
		.amdhsa_exception_fp_ieee_invalid_op 0
		.amdhsa_exception_fp_denorm_src 0
		.amdhsa_exception_fp_ieee_div_zero 0
		.amdhsa_exception_fp_ieee_overflow 0
		.amdhsa_exception_fp_ieee_underflow 0
		.amdhsa_exception_fp_ieee_inexact 0
		.amdhsa_exception_int_div_zero 0
	.end_amdhsa_kernel

amdhsa.kernels:
  - .agpr_count:     0
    .args:
      - .offset:         0
        .size:           200
        .value_kind:     by_value
      - .offset:         200
        .size:           4
        .value_kind:     hidden_block_count_x
      - .offset:         204
        .size:           4
        .value_kind:     hidden_block_count_y
      - .offset:         208
        .size:           4
        .value_kind:     hidden_block_count_z
      - .offset:         212
        .size:           2
        .value_kind:     hidden_group_size_x
      - .offset:         214
        .size:           2
        .value_kind:     hidden_group_size_y
      - .offset:         216
        .size:           2
        .value_kind:     hidden_group_size_z
      - .offset:         218
        .size:           2
        .value_kind:     hidden_remainder_x
      - .offset:         220
        .size:           2
        .value_kind:     hidden_remainder_y
      - .offset:         222
        .size:           2
        .value_kind:     hidden_remainder_z
      - .offset:         240
        .size:           8
        .value_kind:     hidden_global_offset_x
      - .offset:         248
        .size:           8
        .value_kind:     hidden_global_offset_y
      - .offset:         256
        .size:           8
        .value_kind:     hidden_global_offset_z
      - .offset:         264
        .size:           2
        .value_kind:     hidden_grid_dims
      - .offset:         288
        .size:           8
        .value_kind:     hidden_multigrid_sync_arg
      - .offset:         320
        .size:           4
        .value_kind:     hidden_dynamic_lds_size
    .group_segment_fixed_size: 0
    .kernarg_segment_align: 8
    .kernarg_segment_size: 456
    .language:       OpenCL C
    .language_version:
      - 2
      - 0
    .max_flat_workgroup_size: 512
    .name:           _Z8yoco_fwd6Params
    .private_segment_fixed_size: 0
    .sgpr_count:     108
    .sgpr_spill_count: 132
    .symbol:         _Z8yoco_fwd6Params.kd
    .uniform_work_group_size: 1
    .uses_dynamic_stack: false
    .vgpr_count:     256
    .vgpr_spill_count: 0
    .wavefront_size: 64
